# P1 K-loop: tile DMA pieces in saddr form and issued before the fragment ds_reads of each load segment
# baseline (speedup 1.0000x reference)
.LBB0_167:
	s_add_u32 s34, s30, 0xfff80080
	s_addc_u32 s35, s31, -1
	s_cmp_eq_u32 s72, 28
	s_cselect_b32 s37, s25, s35
	s_cselect_b32 s36, s62, s34
	s_cselect_b32 s35, s23, s71
	s_cselect_b32 s34, s63, s70
	s_add_i32 m0, s39, 0xc000
	s_nop 0
	global_load_lds_dwordx4 v136, s[30:31]
	s_add_i32 m0, s39, 0xe000
	s_nop 0
	global_load_lds_dwordx4 v138, s[30:31]
	ds_read_b128 v[144:147], v151
	ds_read_b128 v[156:159], v151 offset:1024
	ds_read_b128 v[160:163], v151 offset:2048
	ds_read_b128 v[164:167], v151 offset:3072
	ds_read_b128 v[168:171], v152
	ds_read_b128 v[172:175], v152 offset:1024
	ds_read_b128 v[176:179], v152 offset:2048
	ds_read_b128 v[180:183], v152 offset:3072
	ds_read_b128 v[184:187], v153
	ds_read_b128 v[188:191], v153 offset:1024
	ds_read_b128 v[192:195], v153 offset:2048
	ds_read_b128 v[196:199], v153 offset:3072
	ds_read_b128 v[200:203], v153 offset:4096
	ds_read_b128 v[204:207], v153 offset:5120
	ds_read_b128 v[208:211], v153 offset:6144
	ds_read_b128 v[212:215], v153 offset:7168
	s_waitcnt vmcnt(8)
	s_waitcnt lgkmcnt(0)
	s_barrier
	s_setprio 1
	s_waitcnt lgkmcnt(0)
	v_mfma_f32_16x16x32_bf16 v[124:127], v[144:147], v[184:187], v[124:127]
	v_mfma_f32_16x16x32_bf16 v[120:123], v[160:163], v[184:187], v[120:123]
	v_mfma_f32_16x16x32_bf16 v[116:119], v[144:147], v[192:195], v[116:119]
	v_mfma_f32_16x16x32_bf16 v[100:103], v[160:163], v[192:195], v[100:103]
	v_mfma_f32_16x16x32_bf16 v[92:95], v[144:147], v[200:203], v[92:95]
	v_mfma_f32_16x16x32_bf16 v[84:87], v[160:163], v[200:203], v[84:87]
	v_mfma_f32_16x16x32_bf16 v[76:79], v[144:147], v[208:211], v[76:79]
	v_mfma_f32_16x16x32_bf16 v[68:71], v[160:163], v[208:211], v[68:71]
	v_mfma_f32_16x16x32_bf16 v[124:127], v[156:159], v[188:191], v[124:127]
	v_mfma_f32_16x16x32_bf16 v[120:123], v[164:167], v[188:191], v[120:123]
	v_mfma_f32_16x16x32_bf16 v[116:119], v[156:159], v[196:199], v[116:119]
	v_mfma_f32_16x16x32_bf16 v[100:103], v[164:167], v[196:199], v[100:103]
	v_mfma_f32_16x16x32_bf16 v[92:95], v[156:159], v[204:207], v[92:95]
	v_mfma_f32_16x16x32_bf16 v[84:87], v[164:167], v[204:207], v[84:87]
	v_mfma_f32_16x16x32_bf16 v[76:79], v[156:159], v[212:215], v[76:79]
	v_mfma_f32_16x16x32_bf16 v[68:71], v[164:167], v[212:215], v[68:71]
	s_setprio 0
	s_setprio 1
	v_mfma_f32_16x16x32_bf16 v[112:115], v[168:171], v[184:187], v[112:115]
	v_mfma_f32_16x16x32_bf16 v[108:111], v[176:179], v[184:187], v[108:111]
	v_mfma_f32_16x16x32_bf16 v[104:107], v[168:171], v[192:195], v[104:107]
	v_mfma_f32_16x16x32_bf16 v[96:99], v[176:179], v[192:195], v[96:99]
	v_mfma_f32_16x16x32_bf16 v[88:91], v[168:171], v[200:203], v[88:91]
	v_mfma_f32_16x16x32_bf16 v[80:83], v[176:179], v[200:203], v[80:83]
	v_mfma_f32_16x16x32_bf16 v[72:75], v[168:171], v[208:211], v[72:75]
	v_mfma_f32_16x16x32_bf16 v[64:67], v[176:179], v[208:211], v[64:67]
	v_mfma_f32_16x16x32_bf16 v[112:115], v[172:175], v[188:191], v[112:115]
	v_mfma_f32_16x16x32_bf16 v[108:111], v[180:183], v[188:191], v[108:111]
	v_mfma_f32_16x16x32_bf16 v[104:107], v[172:175], v[196:199], v[104:107]
	v_mfma_f32_16x16x32_bf16 v[96:99], v[180:183], v[196:199], v[96:99]
	v_mfma_f32_16x16x32_bf16 v[88:91], v[172:175], v[204:207], v[88:91]
	v_mfma_f32_16x16x32_bf16 v[80:83], v[180:183], v[204:207], v[80:83]
	v_mfma_f32_16x16x32_bf16 v[72:75], v[172:175], v[212:215], v[72:75]
	v_mfma_f32_16x16x32_bf16 v[64:67], v[180:183], v[212:215], v[64:67]
	s_setprio 0
	s_barrier
	s_add_i32 s73, s60, s3
	s_mov_b32 m0, s73
	s_nop 0
	global_load_lds_dwordx4 v132, s[34:35]
	s_add_i32 m0, s73, 0x2000
	s_add_u32 s74, s34, 0x80000
	s_addc_u32 s75, s35, 0
	s_add_i32 s73, s61, s3
	global_load_lds_dwordx4 v128, s[34:35]
	s_mov_b32 m0, s73
	s_nop 0
	global_load_lds_dwordx4 v132, s[74:75]
	s_add_i32 m0, s73, 0x2000
	s_nop 0
	global_load_lds_dwordx4 v128, s[74:75]
	s_mov_b32 m0, s39
	s_nop 0
	global_load_lds_dwordx4 v134, s[36:37]
	s_mov_b32 m0, s40
	s_nop 0
	global_load_lds_dwordx4 v130, s[36:37]
	ds_read_b128 v[184:187], v153 offset:16384
	ds_read_b128 v[188:191], v153 offset:17408
	ds_read_b128 v[192:195], v153 offset:18432
	ds_read_b128 v[196:199], v153 offset:19456
	ds_read_b128 v[200:203], v153 offset:20480
	ds_read_b128 v[204:207], v153 offset:21504
	ds_read_b128 v[208:211], v153 offset:22528
	ds_read_b128 v[212:215], v153 offset:23552
	s_waitcnt vmcnt(8)
	s_waitcnt lgkmcnt(0)
	s_barrier
	s_setprio 1
	s_waitcnt lgkmcnt(0)
	v_mfma_f32_16x16x32_bf16 v[60:63], v[144:147], v[184:187], v[60:63]
	v_mfma_f32_16x16x32_bf16 v[52:55], v[160:163], v[184:187], v[52:55]
	v_mfma_f32_16x16x32_bf16 v[44:47], v[144:147], v[192:195], v[44:47]
	v_mfma_f32_16x16x32_bf16 v[36:39], v[160:163], v[192:195], v[36:39]
	v_mfma_f32_16x16x32_bf16 v[28:31], v[144:147], v[200:203], v[28:31]
	v_mfma_f32_16x16x32_bf16 v[20:23], v[160:163], v[200:203], v[20:23]
	v_mfma_f32_16x16x32_bf16 v[12:15], v[144:147], v[208:211], v[12:15]
	v_mfma_f32_16x16x32_bf16 v[4:7], v[160:163], v[208:211], v[4:7]
	v_mfma_f32_16x16x32_bf16 v[60:63], v[156:159], v[188:191], v[60:63]
	v_mfma_f32_16x16x32_bf16 v[52:55], v[164:167], v[188:191], v[52:55]
	v_mfma_f32_16x16x32_bf16 v[44:47], v[156:159], v[196:199], v[44:47]
	v_mfma_f32_16x16x32_bf16 v[36:39], v[164:167], v[196:199], v[36:39]
	v_mfma_f32_16x16x32_bf16 v[28:31], v[156:159], v[204:207], v[28:31]
	v_mfma_f32_16x16x32_bf16 v[20:23], v[164:167], v[204:207], v[20:23]
	v_mfma_f32_16x16x32_bf16 v[12:15], v[156:159], v[212:215], v[12:15]
	v_mfma_f32_16x16x32_bf16 v[4:7], v[164:167], v[212:215], v[4:7]
	s_setprio 0
	s_setprio 1
	v_mfma_f32_16x16x32_bf16 v[56:59], v[168:171], v[184:187], v[56:59]
	v_mfma_f32_16x16x32_bf16 v[48:51], v[176:179], v[184:187], v[48:51]
	v_mfma_f32_16x16x32_bf16 v[40:43], v[168:171], v[192:195], v[40:43]
	v_mfma_f32_16x16x32_bf16 v[32:35], v[176:179], v[192:195], v[32:35]
	v_mfma_f32_16x16x32_bf16 v[24:27], v[168:171], v[200:203], v[24:27]
	v_mfma_f32_16x16x32_bf16 v[16:19], v[176:179], v[200:203], v[16:19]
	v_mfma_f32_16x16x32_bf16 v[8:11], v[168:171], v[208:211], v[8:11]
	v_mfma_f32_16x16x32_bf16 v[0:3], v[176:179], v[208:211], v[0:3]
	v_mfma_f32_16x16x32_bf16 v[56:59], v[172:175], v[188:191], v[56:59]
	v_mfma_f32_16x16x32_bf16 v[48:51], v[180:183], v[188:191], v[48:51]
	v_mfma_f32_16x16x32_bf16 v[40:43], v[172:175], v[196:199], v[40:43]
	v_mfma_f32_16x16x32_bf16 v[32:35], v[180:183], v[196:199], v[32:35]
	v_mfma_f32_16x16x32_bf16 v[24:27], v[172:175], v[204:207], v[24:27]
	v_mfma_f32_16x16x32_bf16 v[16:19], v[180:183], v[204:207], v[16:19]
	v_mfma_f32_16x16x32_bf16 v[8:11], v[172:175], v[212:215], v[8:11]
	v_mfma_f32_16x16x32_bf16 v[0:3], v[180:183], v[212:215], v[0:3]
	s_setprio 0
	s_barrier
	s_add_i32 s73, 0, 0x18000
	s_add_i32 s74, 0, 0x1c000
	s_add_u32 s36, s36, 0x80000
	s_addc_u32 s37, s37, 0
	s_mov_b32 m0, s41
	s_nop 0
	global_load_lds_dwordx4 v134, s[36:37]
	s_mov_b32 m0, s42
	s_nop 0
	global_load_lds_dwordx4 v130, s[36:37]
	v_add_u32_e32 v155, s73, v149
	ds_read_b128 v[144:147], v155
	ds_read_b128 v[156:159], v155 offset:1024
	ds_read_b128 v[160:163], v155 offset:2048
	ds_read_b128 v[164:167], v155 offset:3072
	v_add_u32_e32 v155, s74, v149
	ds_read_b128 v[168:171], v155
	ds_read_b128 v[172:175], v155 offset:1024
	ds_read_b128 v[176:179], v155 offset:2048
	ds_read_b128 v[180:183], v155 offset:3072
	ds_read_b128 v[184:187], v153 offset:32768
	ds_read_b128 v[188:191], v153 offset:33792
	ds_read_b128 v[192:195], v153 offset:34816
	ds_read_b128 v[196:199], v153 offset:35840
	ds_read_b128 v[200:203], v153 offset:36864
	ds_read_b128 v[204:207], v153 offset:37888
	ds_read_b128 v[208:211], v153 offset:38912
	ds_read_b128 v[212:215], v153 offset:39936
	s_waitcnt vmcnt(8)
	s_waitcnt lgkmcnt(0)
	s_barrier
	s_setprio 1
	s_waitcnt lgkmcnt(0)
	v_mfma_f32_16x16x32_bf16 v[124:127], v[144:147], v[184:187], v[124:127]
	v_mfma_f32_16x16x32_bf16 v[120:123], v[160:163], v[184:187], v[120:123]
	v_mfma_f32_16x16x32_bf16 v[116:119], v[144:147], v[192:195], v[116:119]
	v_mfma_f32_16x16x32_bf16 v[100:103], v[160:163], v[192:195], v[100:103]
	v_mfma_f32_16x16x32_bf16 v[92:95], v[144:147], v[200:203], v[92:95]
	v_mfma_f32_16x16x32_bf16 v[84:87], v[160:163], v[200:203], v[84:87]
	v_mfma_f32_16x16x32_bf16 v[76:79], v[144:147], v[208:211], v[76:79]
	v_mfma_f32_16x16x32_bf16 v[68:71], v[160:163], v[208:211], v[68:71]
	v_mfma_f32_16x16x32_bf16 v[124:127], v[156:159], v[188:191], v[124:127]
	v_mfma_f32_16x16x32_bf16 v[120:123], v[164:167], v[188:191], v[120:123]
	v_mfma_f32_16x16x32_bf16 v[116:119], v[156:159], v[196:199], v[116:119]
	v_mfma_f32_16x16x32_bf16 v[100:103], v[164:167], v[196:199], v[100:103]
	v_mfma_f32_16x16x32_bf16 v[92:95], v[156:159], v[204:207], v[92:95]
	v_mfma_f32_16x16x32_bf16 v[84:87], v[164:167], v[204:207], v[84:87]
	v_mfma_f32_16x16x32_bf16 v[76:79], v[156:159], v[212:215], v[76:79]
	v_mfma_f32_16x16x32_bf16 v[68:71], v[164:167], v[212:215], v[68:71]
	s_setprio 0
	s_setprio 1
	v_mfma_f32_16x16x32_bf16 v[112:115], v[168:171], v[184:187], v[112:115]
	v_mfma_f32_16x16x32_bf16 v[108:111], v[176:179], v[184:187], v[108:111]
	v_mfma_f32_16x16x32_bf16 v[104:107], v[168:171], v[192:195], v[104:107]
	v_mfma_f32_16x16x32_bf16 v[96:99], v[176:179], v[192:195], v[96:99]
	v_mfma_f32_16x16x32_bf16 v[88:91], v[168:171], v[200:203], v[88:91]
	v_mfma_f32_16x16x32_bf16 v[80:83], v[176:179], v[200:203], v[80:83]
	v_mfma_f32_16x16x32_bf16 v[72:75], v[168:171], v[208:211], v[72:75]
	v_mfma_f32_16x16x32_bf16 v[64:67], v[176:179], v[208:211], v[64:67]
	v_mfma_f32_16x16x32_bf16 v[112:115], v[172:175], v[188:191], v[112:115]
	v_mfma_f32_16x16x32_bf16 v[108:111], v[180:183], v[188:191], v[108:111]
	v_mfma_f32_16x16x32_bf16 v[104:107], v[172:175], v[196:199], v[104:107]
	v_mfma_f32_16x16x32_bf16 v[96:99], v[180:183], v[196:199], v[96:99]
	v_mfma_f32_16x16x32_bf16 v[88:91], v[172:175], v[204:207], v[88:91]
	v_mfma_f32_16x16x32_bf16 v[80:83], v[180:183], v[204:207], v[80:83]
	v_mfma_f32_16x16x32_bf16 v[72:75], v[172:175], v[212:215], v[72:75]
	v_mfma_f32_16x16x32_bf16 v[64:67], v[180:183], v[212:215], v[64:67]
	s_setprio 0
	s_barrier
	s_add_u32 s100, s36, 0xfff80080
	s_addc_u32 s101, s37, -1
	s_add_i32 s36, s73, s3
	s_add_u32 s98, s34, 0x80
	s_addc_u32 s99, s35, 0
	s_mov_b32 m0, s36
	s_nop 0
	global_load_lds_dwordx4 v132, s[98:99]
	s_add_i32 m0, s36, 0x2000
	s_add_u32 s34, s34, 0x80080
	s_addc_u32 s35, s35, 0
	s_add_i32 s36, s74, s3
	global_load_lds_dwordx4 v128, s[98:99]
	s_mov_b32 m0, s36
	s_nop 0
	global_load_lds_dwordx4 v132, s[34:35]
	s_add_i32 m0, s36, 0x2000
	s_nop 0
	global_load_lds_dwordx4 v128, s[34:35]
	s_mov_b32 m0, s44
	s_nop 0
	global_load_lds_dwordx4 v134, s[100:101]
	s_mov_b32 m0, s45
	s_nop 0
	global_load_lds_dwordx4 v130, s[100:101]
	ds_read_b128 v[184:187], v153 offset:49152
	ds_read_b128 v[188:191], v153 offset:50176
	ds_read_b128 v[192:195], v153 offset:51200
	ds_read_b128 v[196:199], v153 offset:52224
	ds_read_b128 v[200:203], v153 offset:53248
	ds_read_b128 v[204:207], v153 offset:54272
	ds_read_b128 v[208:211], v153 offset:55296
	ds_read_b128 v[212:215], v153 offset:56320
	s_waitcnt vmcnt(8)
	s_waitcnt lgkmcnt(0)
	s_barrier
	s_setprio 1
	s_waitcnt lgkmcnt(0)
	v_mfma_f32_16x16x32_bf16 v[60:63], v[144:147], v[184:187], v[60:63]
	v_mfma_f32_16x16x32_bf16 v[52:55], v[160:163], v[184:187], v[52:55]
	v_mfma_f32_16x16x32_bf16 v[44:47], v[144:147], v[192:195], v[44:47]
	v_mfma_f32_16x16x32_bf16 v[36:39], v[160:163], v[192:195], v[36:39]
	v_mfma_f32_16x16x32_bf16 v[28:31], v[144:147], v[200:203], v[28:31]
	v_mfma_f32_16x16x32_bf16 v[20:23], v[160:163], v[200:203], v[20:23]
	v_mfma_f32_16x16x32_bf16 v[12:15], v[144:147], v[208:211], v[12:15]
	v_mfma_f32_16x16x32_bf16 v[4:7], v[160:163], v[208:211], v[4:7]
	v_mfma_f32_16x16x32_bf16 v[60:63], v[156:159], v[188:191], v[60:63]
	v_mfma_f32_16x16x32_bf16 v[52:55], v[164:167], v[188:191], v[52:55]
	v_mfma_f32_16x16x32_bf16 v[44:47], v[156:159], v[196:199], v[44:47]
	v_mfma_f32_16x16x32_bf16 v[36:39], v[164:167], v[196:199], v[36:39]
	v_mfma_f32_16x16x32_bf16 v[28:31], v[156:159], v[204:207], v[28:31]
	v_mfma_f32_16x16x32_bf16 v[20:23], v[164:167], v[204:207], v[20:23]
	v_mfma_f32_16x16x32_bf16 v[12:15], v[156:159], v[212:215], v[12:15]
	v_mfma_f32_16x16x32_bf16 v[4:7], v[164:167], v[212:215], v[4:7]
	s_setprio 0
	s_setprio 1
	v_mfma_f32_16x16x32_bf16 v[56:59], v[168:171], v[184:187], v[56:59]
	v_mfma_f32_16x16x32_bf16 v[48:51], v[176:179], v[184:187], v[48:51]
	v_mfma_f32_16x16x32_bf16 v[40:43], v[168:171], v[192:195], v[40:43]
	v_mfma_f32_16x16x32_bf16 v[32:35], v[176:179], v[192:195], v[32:35]
	v_mfma_f32_16x16x32_bf16 v[24:27], v[168:171], v[200:203], v[24:27]
	v_mfma_f32_16x16x32_bf16 v[16:19], v[176:179], v[200:203], v[16:19]
	v_mfma_f32_16x16x32_bf16 v[8:11], v[168:171], v[208:211], v[8:11]
	v_mfma_f32_16x16x32_bf16 v[0:3], v[176:179], v[208:211], v[0:3]
	v_mfma_f32_16x16x32_bf16 v[56:59], v[172:175], v[188:191], v[56:59]
	v_mfma_f32_16x16x32_bf16 v[48:51], v[180:183], v[188:191], v[48:51]
	v_mfma_f32_16x16x32_bf16 v[40:43], v[172:175], v[196:199], v[40:43]
	v_mfma_f32_16x16x32_bf16 v[32:35], v[180:183], v[196:199], v[32:35]
	v_mfma_f32_16x16x32_bf16 v[24:27], v[172:175], v[204:207], v[24:27]
	v_mfma_f32_16x16x32_bf16 v[16:19], v[180:183], v[204:207], v[16:19]
	v_mfma_f32_16x16x32_bf16 v[8:11], v[172:175], v[212:215], v[8:11]
	v_mfma_f32_16x16x32_bf16 v[0:3], v[180:183], v[212:215], v[0:3]
	s_setprio 0
	s_barrier
	s_add_i32 s72, s72, 2
	s_add_u32 s30, s30, 0x100
	s_addc_u32 s31, s31, 0
	s_add_u32 s70, s70, 0x100
	s_addc_u32 s71, s71, 0
	s_cmp_gt_u32 s72, 29
	s_cbranch_scc0 .LBB0_167
	s_and_b64 vcc, exec, s[20:21]
	s_cbranch_vccz .LBB0_170
	s_barrier

	.amdhsa_kernel _Z6mk_fwd4Args
		.amdhsa_group_segment_fixed_size 0
		.amdhsa_private_segment_fixed_size 0
		.amdhsa_kernarg_size 448
		.amdhsa_user_sgpr_count 2
		.amdhsa_user_sgpr_dispatch_ptr 0
		.amdhsa_user_sgpr_queue_ptr 0
		.amdhsa_user_sgpr_kernarg_segment_ptr 1
		.amdhsa_user_sgpr_dispatch_id 0
		.amdhsa_user_sgpr_kernarg_preload_length 0
		.amdhsa_user_sgpr_kernarg_preload_offset 0
		.amdhsa_user_sgpr_private_segment_size 0
		.amdhsa_uses_dynamic_stack 0
		.amdhsa_enable_private_segment 0
		.amdhsa_system_sgpr_workgroup_id_x 1
		.amdhsa_system_sgpr_workgroup_id_y 0
		.amdhsa_system_sgpr_workgroup_id_z 0
		.amdhsa_system_sgpr_workgroup_info 0
		.amdhsa_system_vgpr_workitem_id 2
		.amdhsa_next_free_vgpr 251
		.amdhsa_next_free_sgpr 102
		.amdhsa_accum_offset 252
		.amdhsa_reserve_vcc 1
		.amdhsa_float_round_mode_32 0
		.amdhsa_float_round_mode_16_64 0
		.amdhsa_float_denorm_mode_32 3
		.amdhsa_float_denorm_mode_16_64 3
		.amdhsa_dx10_clamp 1
		.amdhsa_ieee_mode 1
		.amdhsa_fp16_overflow 0
		.amdhsa_tg_split 0
		.amdhsa_exception_fp_ieee_invalid_op 0
		.amdhsa_exception_fp_denorm_src 0
		.amdhsa_exception_fp_ieee_div_zero 0
		.amdhsa_exception_fp_ieee_overflow 0
		.amdhsa_exception_fp_ieee_underflow 0
		.amdhsa_exception_fp_ieee_inexact 0
		.amdhsa_exception_int_div_zero 0
	.end_amdhsa_kernel
